# phase-3 tail: cbias partial-sum item loads de-serialised (8 dependent load-wait-fmac steps per iteration -> all loads of the iteration issued together)
# speedup vs baseline: 1.0036x; 1.0030x over previous
.LBB0_694:
	s_nop 1
	v_lshl_add_u64 v[14:15], v[2:3], 0, s[60:61]
	v_lshl_add_u64 v[18:19], v[4:5], 0, s[60:61]
	global_load_dwordx4 v[10:13], v[14:15], off offset:16
	s_nop 0
	global_load_dwordx4 v[14:17], v[14:15], off
	v_add_u32_e32 v9, 8, v9
	global_load_dword v20, v[18:19], off
	global_load_dword v120, v[18:19], off offset:512
	global_load_dword v121, v[18:19], off offset:1024
	global_load_dword v122, v[18:19], off offset:1536
	global_load_dword v123, v[18:19], off offset:2048
	global_load_dword v124, v[18:19], off offset:2560
	global_load_dword v125, v[18:19], off offset:3072
	global_load_dword v126, v[18:19], off offset:3584
	v_cmp_ge_i32_e32 vcc, v9, v8
	v_lshl_add_u64 v[2:3], v[2:3], 0, 32
	v_lshl_add_u64 v[4:5], v[4:5], 0, s[24:25]
	s_or_b64 s[0:1], vcc, s[0:1]
	s_waitcnt vmcnt(0)
	v_fmac_f32_e32 v6, v14, v20
	v_fmac_f32_e32 v6, v15, v120
	v_fmac_f32_e32 v6, v16, v121
	v_fmac_f32_e32 v6, v17, v122
	v_fmac_f32_e32 v6, v10, v123
	v_fmac_f32_e32 v6, v11, v124
	v_fmac_f32_e32 v6, v12, v125
	v_fmac_f32_e32 v6, v13, v126
	s_andn2_b64 exec, exec, s[0:1]
	s_cbranch_execnz .LBB0_694
	s_or_b64 exec, exec, s[0:1]
	s_movk_i32 s0, 0x80
	v_cmp_gt_u32_e32 vcc, s0, v0
	s_movk_i32 s0, 0x7f
	v_cmp_lt_u32_e64 s[0:1], s0, v0
	v_lshlrev_b32_e32 v2, 2, v7
	s_barrier
	s_and_saveexec_b64 s[24:25], s[0:1]
	ds_write_b32 v2, v6
	s_or_b64 exec, exec, s[24:25]
	s_waitcnt lgkmcnt(0)
	s_barrier
	s_and_saveexec_b64 s[0:1], vcc
	s_mov_b32 s59, 0x800000
	s_cbranch_execz .LBB0_699
	ds_read_b32 v4, v2
	v_lshl_or_b32 v0, s26, 7, v0
	v_lshl_add_u64 v[2:3], v[0:1], 2, s[16:17]
	s_waitcnt lgkmcnt(0)
	v_add_f32_e32 v0, v6, v4
	global_store_dword v[2:3], v0, off
